# v58 plus one-off s_sleep stagger of the second workgroup on each CU before the two GEMM main loops
# speedup vs baseline: 1.0037x; 1.0037x over previous
.LBB0_88:
	s_lshl_b32 s11, s16, 7
	s_and_b32 s27, s11, 0x1f80
	v_add_u32_e32 v5, s27, v86
	v_mad_i64_i32 v[2:3], s[38:39], v5, s13, 0
	s_lshl_b32 s11, s16, 1
	s_and_b32 s38, s11, 0xffffff80
	v_add_u32_e32 v4, s38, v86
	v_add_u32_e32 v14, 0, v87
	v_min_i32_e32 v6, 0x3ff, v4
	v_readfirstlane_b32 s11, v14
	v_add_u32_e32 v15, 0x8000, v14
	v_mad_i64_i32 v[6:7], s[40:41], v6, s13, 0
	v_lshl_add_u64 v[2:3], v[2:3], 1, v[66:67]
	s_mov_b32 m0, s11
	v_readfirstlane_b32 s11, v15
	v_add_u32_e32 v15, 0x1000, v14
	v_lshl_add_u64 v[6:7], v[6:7], 1, v[68:69]
	global_load_lds_dwordx4 v[2:3], off
	s_mov_b32 m0, s11
	v_readfirstlane_b32 s11, v15
	v_add_u32_e32 v8, 32, v4
	global_load_lds_dwordx4 v[6:7], off
	v_lshl_add_u64 v[6:7], v[2:3], 0, s[92:93]
	s_mov_b32 m0, s11
	v_min_i32_e32 v8, 0x3ff, v8
	global_load_lds_dwordx4 v[6:7], off
	v_add_u32_e32 v6, 0x9000, v14
	v_mad_i64_i32 v[8:9], s[40:41], v8, s13, 0
	v_readfirstlane_b32 s11, v6
	v_lshl_add_u64 v[8:9], v[8:9], 1, v[68:69]
	s_mov_b32 m0, s11
	s_mov_b32 s11, s93
	global_load_lds_dwordx4 v[8:9], off
	v_add_u32_e32 v8, 0x2000, v14
	v_lshl_add_u64 v[6:7], v[2:3], 0, s[10:11]
	v_readfirstlane_b32 s11, v8
	v_add_u32_e32 v10, 64, v4
	s_mov_b32 m0, s11
	v_min_i32_e32 v10, 0x3ff, v10
	global_load_lds_dwordx4 v[6:7], off
	v_add_u32_e32 v6, 0xa000, v14
	v_mad_i64_i32 v[10:11], s[40:41], v10, s13, 0
	v_readfirstlane_b32 s11, v6
	v_add_u32_e32 v6, 0x3000, v14
	v_lshl_add_u64 v[10:11], v[10:11], 1, v[68:69]
	s_mov_b32 m0, s11
	s_mov_b32 s37, s93
	v_readfirstlane_b32 s11, v6
	v_add_u32_e32 v12, 0x60, v4
	global_load_lds_dwordx4 v[10:11], off
	v_lshl_add_u64 v[2:3], v[2:3], 0, s[36:37]
	s_mov_b32 m0, s11
	v_min_i32_e32 v12, 0x3ff, v12
	global_load_lds_dwordx4 v[2:3], off
	v_add_u32_e32 v2, 0xb000, v14
	v_mad_i64_i32 v[12:13], s[40:41], v12, s13, 0
	v_readfirstlane_b32 s11, v2
	v_lshl_add_u64 v[12:13], v[12:13], 1, v[68:69]
	s_mov_b32 m0, s11
	v_mov_b64_e32 v[2:3], s[4:5]
	global_load_lds_dwordx4 v[12:13], off
	v_mad_i64_i32 v[70:71], s[40:41], s25, v5, v[2:3]
	v_lshlrev_b32_e32 v5, 1, v5
	v_add_u32_e32 v6, 64, v5
	v_mad_i64_i32 v[72:73], s[40:41], s13, v6, v[2:3]
	v_add_u32_e32 v6, 0x80, v5
	v_add_u32_e32 v5, 0xc0, v5
	v_mad_i64_i32 v[76:77], s[40:41], s13, v5, v[2:3]
	v_ashrrev_i32_e32 v5, 31, v4
	s_mov_b64 s[42:43], 0x3ff
	v_cmp_gt_i64_e32 vcc, s[42:43], v[4:5]
	v_mad_i64_i32 v[74:75], s[40:41], s13, v6, v[2:3]
	s_nop 0
	v_cndmask_b32_e32 v4, v199, v4, vcc
	v_mov_b64_e32 v[2:3], s[6:7]
	v_mad_i64_i32 v[78:79], s[40:41], s25, v4, v[2:3]
	v_add_u32_e32 v4, s38, v97
	v_ashrrev_i32_e32 v5, 31, v4
	v_cmp_gt_i64_e32 vcc, s[42:43], v[4:5]
	s_waitcnt vmcnt(0)
	s_movk_i32 s11, 0x4000
	s_waitcnt vmcnt(0) lgkmcnt(0)
	v_cndmask_b32_e32 v4, v199, v4, vcc
	v_mad_i64_i32 v[80:81], s[40:41], s25, v4, v[2:3]
	v_add_u32_e32 v4, s38, v98
	v_ashrrev_i32_e32 v5, 31, v4
	v_cmp_gt_i64_e32 vcc, s[42:43], v[4:5]
	s_barrier
	s_nop 0
	v_cndmask_b32_e32 v4, v199, v4, vcc
	v_mad_i64_i32 v[82:83], s[40:41], s25, v4, v[2:3]
	v_add_u32_e32 v4, s38, v99
	v_ashrrev_i32_e32 v5, 31, v4
	v_cmp_gt_i64_e32 vcc, s[42:43], v[4:5]
	s_nop 1
	v_cndmask_b32_e32 v4, v199, v4, vcc
	v_mad_i64_i32 v[84:85], s[40:41], s25, v4, v[2:3]
	v_mov_b32_e32 v2, 0
	v_mov_b32_e32 v3, v2
	v_mov_b32_e32 v4, v2
	v_mov_b32_e32 v5, v2
	v_mov_b32_e32 v6, v2
	v_mov_b32_e32 v7, v2
	v_mov_b32_e32 v8, v2
	v_mov_b32_e32 v9, v2
	v_mov_b32_e32 v10, v2
	v_mov_b32_e32 v11, v2
	v_mov_b32_e32 v12, v2
	v_mov_b32_e32 v13, v2
	v_mov_b32_e32 v14, v2
	v_mov_b32_e32 v15, v2
	v_mov_b32_e32 v16, v2
	v_mov_b32_e32 v17, v2
	v_mov_b32_e32 v18, v2
	v_mov_b32_e32 v19, v2
	v_mov_b32_e32 v20, v2
	v_mov_b32_e32 v21, v2
	v_mov_b32_e32 v22, v2
	v_mov_b32_e32 v23, v2
	v_mov_b32_e32 v24, v2
	v_mov_b32_e32 v25, v2
	v_mov_b32_e32 v26, v2
	v_mov_b32_e32 v27, v2
	v_mov_b32_e32 v28, v2
	v_mov_b32_e32 v29, v2
	v_mov_b32_e32 v30, v2
	v_mov_b32_e32 v31, v2
	v_mov_b32_e32 v32, v2
	v_mov_b32_e32 v33, v2
	v_mov_b32_e32 v34, v2
	v_mov_b32_e32 v35, v2
	v_mov_b32_e32 v36, v2
	v_mov_b32_e32 v37, v2
	v_mov_b32_e32 v38, v2
	v_mov_b32_e32 v39, v2
	v_mov_b32_e32 v40, v2
	v_mov_b32_e32 v41, v2
	v_mov_b32_e32 v42, v2
	v_mov_b32_e32 v43, v2
	v_mov_b32_e32 v44, v2
	v_mov_b32_e32 v45, v2
	v_mov_b32_e32 v46, v2
	v_mov_b32_e32 v47, v2
	v_mov_b32_e32 v48, v2
	v_mov_b32_e32 v49, v2
	v_mov_b32_e32 v50, v2
	v_mov_b32_e32 v51, v2
	v_mov_b32_e32 v52, v2
	v_mov_b32_e32 v53, v2
	v_mov_b32_e32 v54, v2
	v_mov_b32_e32 v55, v2
	v_mov_b32_e32 v56, v2
	v_mov_b32_e32 v57, v2
	v_mov_b32_e32 v58, v2
	v_mov_b32_e32 v59, v2
	v_mov_b32_e32 v60, v2
	v_mov_b32_e32 v61, v2
	v_mov_b32_e32 v62, v2
	v_mov_b32_e32 v63, v2
	v_mov_b32_e32 v64, v2
	v_mov_b32_e32 v65, v2
	v_readfirstlane_b32 s37, v87
	s_lshr_b32 s39, s22, 15
	s_sub_u32 s39, s39, 1
	v_lshl_add_u64 v[70:71], v[70:71], 0, v[130:131]
	v_lshl_add_u64 v[72:73], v[72:73], 0, v[130:131]
	v_lshl_add_u64 v[74:75], v[74:75], 0, v[130:131]
	v_lshl_add_u64 v[76:77], v[76:77], 0, v[130:131]
	v_lshl_add_u64 v[78:79], v[78:79], 0, v[130:131]
	v_lshl_add_u64 v[80:81], v[80:81], 0, v[130:131]
	v_lshl_add_u64 v[82:83], v[82:83], 0, v[130:131]
	v_lshl_add_u64 v[84:85], v[84:85], 0, v[130:131]
	v_add3_u32 v116, v88, v89, v90
	v_add_u32_e32 v120, v88, v92
	v_add3_u32 v117, v93, v89, v90
	v_add_u32_e32 v121, v93, v92
	v_add3_u32 v118, v94, v89, v90
	v_add_u32_e32 v122, v94, v92
	v_add3_u32 v119, v95, v89, v90
	v_add_u32_e32 v123, v95, v92
	ds_read_b128 v[132:135], v116
	ds_read_b128 v[136:139], v116 offset:4096
	ds_read_b128 v[140:143], v120 offset:32768
	ds_read_b128 v[144:147], v120 offset:40960
	v_readlane_b32 s100, v255, 49
	s_cmp_eq_u32 s100, -1
	s_cbranch_scc1 .Lstag_g2
	s_bitcmp1_b32 s100, 8
	s_cbranch_scc0 .Lstag_g2
	s_sleep 8
.Lstag_g2:
.Lg2_loop:
	ds_read_b128 v[148:151], v117
	ds_read_b128 v[152:155], v117 offset:4096
	ds_read_b128 v[156:159], v121 offset:32768
	ds_read_b128 v[160:163], v121 offset:40960
	s_waitcnt lgkmcnt(4)
	v_mfma_f32_32x32x16_bf16 v[50:65], v[132:135], v[140:143], v[50:65]
	s_add_u32 m0, s37, 0x4000
	s_nop 0
	global_load_lds_dwordx4 v[70:71], off
	v_lshl_add_u64 v[70:71], v[70:71], 0, s[98:99]
	v_mfma_f32_32x32x16_bf16 v[34:49], v[132:135], v[144:147], v[34:49]
	s_add_u32 m0, s37, 0xc000
	s_nop 0
	global_load_lds_dwordx4 v[78:79], off
	v_lshl_add_u64 v[78:79], v[78:79], 0, s[98:99]
	v_mfma_f32_32x32x16_bf16 v[18:33], v[136:139], v[140:143], v[18:33]
	s_add_u32 m0, s37, 0x5000
	s_nop 0
	global_load_lds_dwordx4 v[72:73], off
	v_lshl_add_u64 v[72:73], v[72:73], 0, s[98:99]
	v_mfma_f32_32x32x16_bf16 v[2:17], v[136:139], v[144:147], v[2:17]
	ds_read_b128 v[132:135], v118
	ds_read_b128 v[136:139], v118 offset:4096
	ds_read_b128 v[140:143], v122 offset:32768
	ds_read_b128 v[144:147], v122 offset:40960
	s_waitcnt lgkmcnt(4)
	v_mfma_f32_32x32x16_bf16 v[50:65], v[148:151], v[156:159], v[50:65]
	s_add_u32 m0, s37, 0xd000
	s_nop 0
	global_load_lds_dwordx4 v[80:81], off
	v_lshl_add_u64 v[80:81], v[80:81], 0, s[98:99]
	v_mfma_f32_32x32x16_bf16 v[34:49], v[148:151], v[160:163], v[34:49]
	s_add_u32 m0, s37, 0x6000
	s_nop 0
	global_load_lds_dwordx4 v[74:75], off
	v_lshl_add_u64 v[74:75], v[74:75], 0, s[98:99]
	v_mfma_f32_32x32x16_bf16 v[18:33], v[152:155], v[156:159], v[18:33]
	s_add_u32 m0, s37, 0xe000
	s_nop 0
	global_load_lds_dwordx4 v[82:83], off
	v_lshl_add_u64 v[82:83], v[82:83], 0, s[98:99]
	v_mfma_f32_32x32x16_bf16 v[2:17], v[152:155], v[160:163], v[2:17]
	ds_read_b128 v[148:151], v119
	ds_read_b128 v[152:155], v119 offset:4096
	ds_read_b128 v[156:159], v123 offset:32768
	ds_read_b128 v[160:163], v123 offset:40960
	s_waitcnt lgkmcnt(4)
	v_mfma_f32_32x32x16_bf16 v[50:65], v[132:135], v[140:143], v[50:65]
	s_add_u32 m0, s37, 0x7000
	s_nop 0
	global_load_lds_dwordx4 v[76:77], off
	v_lshl_add_u64 v[76:77], v[76:77], 0, s[98:99]
	v_mfma_f32_32x32x16_bf16 v[34:49], v[132:135], v[144:147], v[34:49]
	s_add_u32 m0, s37, 0xf000
	s_nop 0
	global_load_lds_dwordx4 v[84:85], off
	v_lshl_add_u64 v[84:85], v[84:85], 0, s[98:99]
	v_mfma_f32_32x32x16_bf16 v[18:33], v[136:139], v[140:143], v[18:33]
	v_mfma_f32_32x32x16_bf16 v[2:17], v[136:139], v[144:147], v[2:17]
	s_waitcnt vmcnt(0) lgkmcnt(0)
	s_barrier
	ds_read_b128 v[132:135], v116 offset:16384
	ds_read_b128 v[136:139], v116 offset:20480
	ds_read_b128 v[140:143], v120 offset:49152
	ds_read_b128 v[144:147], v120 offset:57344
	v_mfma_f32_32x32x16_bf16 v[50:65], v[148:151], v[156:159], v[50:65]
	v_mfma_f32_32x32x16_bf16 v[34:49], v[148:151], v[160:163], v[34:49]
	v_mfma_f32_32x32x16_bf16 v[18:33], v[152:155], v[156:159], v[18:33]
	v_mfma_f32_32x32x16_bf16 v[2:17], v[152:155], v[160:163], v[2:17]
	ds_read_b128 v[148:151], v117 offset:16384
	ds_read_b128 v[152:155], v117 offset:20480
	ds_read_b128 v[156:159], v121 offset:49152
	ds_read_b128 v[160:163], v121 offset:57344
	s_waitcnt lgkmcnt(4)
	v_mfma_f32_32x32x16_bf16 v[50:65], v[132:135], v[140:143], v[50:65]
	s_mov_b32 m0, s37
	s_nop 0
	global_load_lds_dwordx4 v[70:71], off
	v_lshl_add_u64 v[70:71], v[70:71], 0, s[98:99]
	v_mfma_f32_32x32x16_bf16 v[34:49], v[132:135], v[144:147], v[34:49]
	s_add_u32 m0, s37, 0x8000
	s_nop 0
	global_load_lds_dwordx4 v[78:79], off
	v_lshl_add_u64 v[78:79], v[78:79], 0, s[98:99]
	v_mfma_f32_32x32x16_bf16 v[18:33], v[136:139], v[140:143], v[18:33]
	s_add_u32 m0, s37, 0x1000
	s_nop 0
	global_load_lds_dwordx4 v[72:73], off
	v_lshl_add_u64 v[72:73], v[72:73], 0, s[98:99]
	v_mfma_f32_32x32x16_bf16 v[2:17], v[136:139], v[144:147], v[2:17]
	ds_read_b128 v[132:135], v118 offset:16384
	ds_read_b128 v[136:139], v118 offset:20480
	ds_read_b128 v[140:143], v122 offset:49152
	ds_read_b128 v[144:147], v122 offset:57344
	s_waitcnt lgkmcnt(4)
	v_mfma_f32_32x32x16_bf16 v[50:65], v[148:151], v[156:159], v[50:65]
	s_add_u32 m0, s37, 0x9000
	s_nop 0
	global_load_lds_dwordx4 v[80:81], off
	v_lshl_add_u64 v[80:81], v[80:81], 0, s[98:99]
	v_mfma_f32_32x32x16_bf16 v[34:49], v[148:151], v[160:163], v[34:49]
	s_add_u32 m0, s37, 0x2000
	s_nop 0
	global_load_lds_dwordx4 v[74:75], off
	v_lshl_add_u64 v[74:75], v[74:75], 0, s[98:99]
	v_mfma_f32_32x32x16_bf16 v[18:33], v[152:155], v[156:159], v[18:33]
	s_add_u32 m0, s37, 0xa000
	s_nop 0
	global_load_lds_dwordx4 v[82:83], off
	v_lshl_add_u64 v[82:83], v[82:83], 0, s[98:99]
	v_mfma_f32_32x32x16_bf16 v[2:17], v[152:155], v[160:163], v[2:17]
	ds_read_b128 v[148:151], v119 offset:16384
	ds_read_b128 v[152:155], v119 offset:20480
	ds_read_b128 v[156:159], v123 offset:49152
	ds_read_b128 v[160:163], v123 offset:57344
	s_waitcnt lgkmcnt(4)
	v_mfma_f32_32x32x16_bf16 v[50:65], v[132:135], v[140:143], v[50:65]
	s_add_u32 m0, s37, 0x3000
	s_nop 0
	global_load_lds_dwordx4 v[76:77], off
	v_lshl_add_u64 v[76:77], v[76:77], 0, s[98:99]
	v_mfma_f32_32x32x16_bf16 v[34:49], v[132:135], v[144:147], v[34:49]
	s_add_u32 m0, s37, 0xb000
	s_nop 0
	global_load_lds_dwordx4 v[84:85], off
	v_lshl_add_u64 v[84:85], v[84:85], 0, s[98:99]
	v_mfma_f32_32x32x16_bf16 v[18:33], v[136:139], v[140:143], v[18:33]
	v_mfma_f32_32x32x16_bf16 v[2:17], v[136:139], v[144:147], v[2:17]
	s_waitcnt vmcnt(0) lgkmcnt(0)
	s_barrier
	ds_read_b128 v[132:135], v116
	ds_read_b128 v[136:139], v116 offset:4096
	ds_read_b128 v[140:143], v120 offset:32768
	ds_read_b128 v[144:147], v120 offset:40960
	v_mfma_f32_32x32x16_bf16 v[50:65], v[148:151], v[156:159], v[50:65]
	v_mfma_f32_32x32x16_bf16 v[34:49], v[148:151], v[160:163], v[34:49]
	v_mfma_f32_32x32x16_bf16 v[18:33], v[152:155], v[156:159], v[18:33]
	v_mfma_f32_32x32x16_bf16 v[2:17], v[152:155], v[160:163], v[2:17]
	s_sub_u32 s39, s39, 1
	s_cmp_lg_u32 s39, 0
	s_cbranch_scc1 .Lg2_loop
	ds_read_b128 v[148:151], v117
	ds_read_b128 v[152:155], v117 offset:4096
	ds_read_b128 v[156:159], v121 offset:32768
	ds_read_b128 v[160:163], v121 offset:40960
	s_waitcnt lgkmcnt(4)
	v_mfma_f32_32x32x16_bf16 v[50:65], v[132:135], v[140:143], v[50:65]
	s_add_u32 m0, s37, 0x4000
	s_nop 0
	global_load_lds_dwordx4 v[70:71], off
	v_lshl_add_u64 v[70:71], v[70:71], 0, s[98:99]
	v_mfma_f32_32x32x16_bf16 v[34:49], v[132:135], v[144:147], v[34:49]
	s_add_u32 m0, s37, 0xc000
	s_nop 0
	global_load_lds_dwordx4 v[78:79], off
	v_lshl_add_u64 v[78:79], v[78:79], 0, s[98:99]
	v_mfma_f32_32x32x16_bf16 v[18:33], v[136:139], v[140:143], v[18:33]
	s_add_u32 m0, s37, 0x5000
	s_nop 0
	global_load_lds_dwordx4 v[72:73], off
	v_lshl_add_u64 v[72:73], v[72:73], 0, s[98:99]
	v_mfma_f32_32x32x16_bf16 v[2:17], v[136:139], v[144:147], v[2:17]
	ds_read_b128 v[132:135], v118
	ds_read_b128 v[136:139], v118 offset:4096
	ds_read_b128 v[140:143], v122 offset:32768
	ds_read_b128 v[144:147], v122 offset:40960
	s_waitcnt lgkmcnt(4)
	v_mfma_f32_32x32x16_bf16 v[50:65], v[148:151], v[156:159], v[50:65]
	s_add_u32 m0, s37, 0xd000
	s_nop 0
	global_load_lds_dwordx4 v[80:81], off
	v_lshl_add_u64 v[80:81], v[80:81], 0, s[98:99]
	v_mfma_f32_32x32x16_bf16 v[34:49], v[148:151], v[160:163], v[34:49]
	s_add_u32 m0, s37, 0x6000
	s_nop 0
	global_load_lds_dwordx4 v[74:75], off
	v_lshl_add_u64 v[74:75], v[74:75], 0, s[98:99]
	v_mfma_f32_32x32x16_bf16 v[18:33], v[152:155], v[156:159], v[18:33]
	s_add_u32 m0, s37, 0xe000
	s_nop 0
	global_load_lds_dwordx4 v[82:83], off
	v_lshl_add_u64 v[82:83], v[82:83], 0, s[98:99]
	v_mfma_f32_32x32x16_bf16 v[2:17], v[152:155], v[160:163], v[2:17]
	ds_read_b128 v[148:151], v119
	ds_read_b128 v[152:155], v119 offset:4096
	ds_read_b128 v[156:159], v123 offset:32768
	ds_read_b128 v[160:163], v123 offset:40960
	s_waitcnt lgkmcnt(4)
	v_mfma_f32_32x32x16_bf16 v[50:65], v[132:135], v[140:143], v[50:65]
	s_add_u32 m0, s37, 0x7000
	s_nop 0
	global_load_lds_dwordx4 v[76:77], off
	v_lshl_add_u64 v[76:77], v[76:77], 0, s[98:99]
	v_mfma_f32_32x32x16_bf16 v[34:49], v[132:135], v[144:147], v[34:49]
	s_add_u32 m0, s37, 0xf000
	s_nop 0
	global_load_lds_dwordx4 v[84:85], off
	v_lshl_add_u64 v[84:85], v[84:85], 0, s[98:99]
	v_mfma_f32_32x32x16_bf16 v[18:33], v[136:139], v[140:143], v[18:33]
	v_mfma_f32_32x32x16_bf16 v[2:17], v[136:139], v[144:147], v[2:17]
	s_waitcnt vmcnt(0) lgkmcnt(0)
	s_barrier
	ds_read_b128 v[132:135], v116 offset:16384
	ds_read_b128 v[136:139], v116 offset:20480
	ds_read_b128 v[140:143], v120 offset:49152
	ds_read_b128 v[144:147], v120 offset:57344
	v_mfma_f32_32x32x16_bf16 v[50:65], v[148:151], v[156:159], v[50:65]
	v_mfma_f32_32x32x16_bf16 v[34:49], v[148:151], v[160:163], v[34:49]
	v_mfma_f32_32x32x16_bf16 v[18:33], v[152:155], v[156:159], v[18:33]
	v_mfma_f32_32x32x16_bf16 v[2:17], v[152:155], v[160:163], v[2:17]
	ds_read_b128 v[148:151], v117 offset:16384
	ds_read_b128 v[152:155], v117 offset:20480
	ds_read_b128 v[156:159], v121 offset:49152
	ds_read_b128 v[160:163], v121 offset:57344
	s_waitcnt lgkmcnt(4)
	v_mfma_f32_32x32x16_bf16 v[50:65], v[132:135], v[140:143], v[50:65]
	v_mfma_f32_32x32x16_bf16 v[34:49], v[132:135], v[144:147], v[34:49]
	v_mfma_f32_32x32x16_bf16 v[18:33], v[136:139], v[140:143], v[18:33]
	v_mfma_f32_32x32x16_bf16 v[2:17], v[136:139], v[144:147], v[2:17]
	ds_read_b128 v[132:135], v118 offset:16384
	ds_read_b128 v[136:139], v118 offset:20480
	ds_read_b128 v[140:143], v122 offset:49152
	ds_read_b128 v[144:147], v122 offset:57344
	s_waitcnt lgkmcnt(4)
	v_mfma_f32_32x32x16_bf16 v[50:65], v[148:151], v[156:159], v[50:65]
	v_mfma_f32_32x32x16_bf16 v[34:49], v[148:151], v[160:163], v[34:49]
	v_mfma_f32_32x32x16_bf16 v[18:33], v[152:155], v[156:159], v[18:33]
	v_mfma_f32_32x32x16_bf16 v[2:17], v[152:155], v[160:163], v[2:17]
	ds_read_b128 v[148:151], v119 offset:16384
	ds_read_b128 v[152:155], v119 offset:20480
	ds_read_b128 v[156:159], v123 offset:49152
	ds_read_b128 v[160:163], v123 offset:57344
	s_waitcnt lgkmcnt(4)
	v_mfma_f32_32x32x16_bf16 v[50:65], v[132:135], v[140:143], v[50:65]
	v_mfma_f32_32x32x16_bf16 v[34:49], v[132:135], v[144:147], v[34:49]
	v_mfma_f32_32x32x16_bf16 v[18:33], v[136:139], v[140:143], v[18:33]
	v_mfma_f32_32x32x16_bf16 v[2:17], v[136:139], v[144:147], v[2:17]
	s_waitcnt vmcnt(0) lgkmcnt(0)
	s_barrier
	v_mfma_f32_32x32x16_bf16 v[50:65], v[148:151], v[156:159], v[50:65]
	v_mfma_f32_32x32x16_bf16 v[34:49], v[148:151], v[160:163], v[34:49]
	v_mfma_f32_32x32x16_bf16 v[18:33], v[152:155], v[156:159], v[18:33]
	v_mfma_f32_32x32x16_bf16 v[2:17], v[152:155], v[160:163], v[2:17]
	v_or_b32_e32 v70, s38, v91
	v_add_u32_e32 v72, s27, v96
	v_readlane_b32 s38, v253, 18
	v_readlane_b32 s39, v253, 19
	s_nop 15
	v_lshlrev_b32_e32 v72, 11, v72
	v_lshl_add_u32 v70, v70, 1, v72
	v_bfe_u32 v73, v50, 16, 1
	v_add3_u32 v73, v50, v73, s26
	global_store_short_d16_hi v70, v73, s[38:39]
	v_bfe_u32 v74, v51, 16, 1
	v_add3_u32 v74, v51, v74, s26
	global_store_short_d16_hi v70, v74, s[38:39] offset:2048
	v_bfe_u32 v75, v34, 16, 1
	v_add3_u32 v75, v34, v75, s26
	global_store_short_d16_hi v70, v75, s[38:39] offset:128
	v_bfe_u32 v76, v35, 16, 1
	v_add3_u32 v76, v35, v76, s26
	global_store_short_d16_hi v70, v76, s[38:39] offset:2176
	v_add_u32_e32 v72, 0x1000, v70
	v_bfe_u32 v77, v52, 16, 1
	v_add3_u32 v77, v52, v77, s26
	global_store_short_d16_hi v72, v77, s[38:39]
	v_bfe_u32 v78, v53, 16, 1
	v_add3_u32 v78, v53, v78, s26
	global_store_short_d16_hi v72, v78, s[38:39] offset:2048
	v_bfe_u32 v79, v36, 16, 1
	v_add3_u32 v79, v36, v79, s26
	global_store_short_d16_hi v72, v79, s[38:39] offset:128
	v_bfe_u32 v80, v37, 16, 1
	v_add3_u32 v80, v37, v80, s26
	global_store_short_d16_hi v72, v80, s[38:39] offset:2176
	v_add_u32_e32 v71, 0x4000, v70
	v_bfe_u32 v73, v54, 16, 1
	v_add3_u32 v73, v54, v73, s26
	global_store_short_d16_hi v71, v73, s[38:39]
	v_bfe_u32 v74, v55, 16, 1
	v_add3_u32 v74, v55, v74, s26
	global_store_short_d16_hi v71, v74, s[38:39] offset:2048
	v_bfe_u32 v75, v38, 16, 1
	v_add3_u32 v75, v38, v75, s26
	global_store_short_d16_hi v71, v75, s[38:39] offset:128
	v_bfe_u32 v76, v39, 16, 1
	v_add3_u32 v76, v39, v76, s26
	global_store_short_d16_hi v71, v76, s[38:39] offset:2176
	v_add_u32_e32 v72, 0x5000, v70
	v_bfe_u32 v77, v56, 16, 1
	v_add3_u32 v77, v56, v77, s26
	global_store_short_d16_hi v72, v77, s[38:39]
	v_bfe_u32 v78, v57, 16, 1
	v_add3_u32 v78, v57, v78, s26
	global_store_short_d16_hi v72, v78, s[38:39] offset:2048
	v_bfe_u32 v79, v40, 16, 1
	v_add3_u32 v79, v40, v79, s26
	global_store_short_d16_hi v72, v79, s[38:39] offset:128
	v_bfe_u32 v80, v41, 16, 1
	v_add3_u32 v80, v41, v80, s26
	global_store_short_d16_hi v72, v80, s[38:39] offset:2176
	v_add_u32_e32 v71, 0x8000, v70
	v_bfe_u32 v73, v58, 16, 1
	v_add3_u32 v73, v58, v73, s26
	global_store_short_d16_hi v71, v73, s[38:39]
	v_bfe_u32 v74, v59, 16, 1
	v_add3_u32 v74, v59, v74, s26
	global_store_short_d16_hi v71, v74, s[38:39] offset:2048
	v_bfe_u32 v75, v42, 16, 1
	v_add3_u32 v75, v42, v75, s26
	global_store_short_d16_hi v71, v75, s[38:39] offset:128
	v_bfe_u32 v76, v43, 16, 1
	v_add3_u32 v76, v43, v76, s26
	global_store_short_d16_hi v71, v76, s[38:39] offset:2176
	v_add_u32_e32 v72, 0x9000, v70
	v_bfe_u32 v77, v60, 16, 1
	v_add3_u32 v77, v60, v77, s26
	global_store_short_d16_hi v72, v77, s[38:39]
	v_bfe_u32 v78, v61, 16, 1
	v_add3_u32 v78, v61, v78, s26
	global_store_short_d16_hi v72, v78, s[38:39] offset:2048
	v_bfe_u32 v79, v44, 16, 1
	v_add3_u32 v79, v44, v79, s26
	global_store_short_d16_hi v72, v79, s[38:39] offset:128
	v_bfe_u32 v80, v45, 16, 1
	v_add3_u32 v80, v45, v80, s26
	global_store_short_d16_hi v72, v80, s[38:39] offset:2176
	v_add_u32_e32 v71, 0xc000, v70
	v_bfe_u32 v73, v62, 16, 1
	v_add3_u32 v73, v62, v73, s26
	global_store_short_d16_hi v71, v73, s[38:39]
	v_bfe_u32 v74, v63, 16, 1
	v_add3_u32 v74, v63, v74, s26
	global_store_short_d16_hi v71, v74, s[38:39] offset:2048
	v_bfe_u32 v75, v46, 16, 1
	v_add3_u32 v75, v46, v75, s26
	global_store_short_d16_hi v71, v75, s[38:39] offset:128
	v_bfe_u32 v76, v47, 16, 1
	v_add3_u32 v76, v47, v76, s26
	global_store_short_d16_hi v71, v76, s[38:39] offset:2176
	v_add_u32_e32 v72, 0xd000, v70
	v_bfe_u32 v77, v64, 16, 1
	v_add3_u32 v77, v64, v77, s26
	global_store_short_d16_hi v72, v77, s[38:39]
	v_bfe_u32 v78, v65, 16, 1
	v_add3_u32 v78, v65, v78, s26
	global_store_short_d16_hi v72, v78, s[38:39] offset:2048
	v_bfe_u32 v79, v48, 16, 1
	v_add3_u32 v79, v48, v79, s26
	global_store_short_d16_hi v72, v79, s[38:39] offset:128
	v_bfe_u32 v80, v49, 16, 1
	v_add3_u32 v80, v49, v80, s26
	global_store_short_d16_hi v72, v80, s[38:39] offset:2176
	v_add_u32_e32 v71, 0x10000, v70
	v_bfe_u32 v73, v18, 16, 1
	v_add3_u32 v73, v18, v73, s26
	global_store_short_d16_hi v71, v73, s[38:39]
	v_bfe_u32 v74, v19, 16, 1
	v_add3_u32 v74, v19, v74, s26
	global_store_short_d16_hi v71, v74, s[38:39] offset:2048
	v_bfe_u32 v75, v2, 16, 1
	v_add3_u32 v75, v2, v75, s26
	global_store_short_d16_hi v71, v75, s[38:39] offset:128
	v_bfe_u32 v76, v3, 16, 1
	v_add3_u32 v76, v3, v76, s26
	global_store_short_d16_hi v71, v76, s[38:39] offset:2176
	v_add_u32_e32 v72, 0x11000, v70
	v_bfe_u32 v77, v20, 16, 1
	v_add3_u32 v77, v20, v77, s26
	global_store_short_d16_hi v72, v77, s[38:39]
	v_bfe_u32 v78, v21, 16, 1
	v_add3_u32 v78, v21, v78, s26
	global_store_short_d16_hi v72, v78, s[38:39] offset:2048
	v_bfe_u32 v79, v4, 16, 1
	v_add3_u32 v79, v4, v79, s26
	global_store_short_d16_hi v72, v79, s[38:39] offset:128
	v_bfe_u32 v80, v5, 16, 1
	v_add3_u32 v80, v5, v80, s26
	global_store_short_d16_hi v72, v80, s[38:39] offset:2176
	v_add_u32_e32 v71, 0x14000, v70
	v_bfe_u32 v73, v22, 16, 1
	v_add3_u32 v73, v22, v73, s26
	global_store_short_d16_hi v71, v73, s[38:39]
	v_bfe_u32 v74, v23, 16, 1
	v_add3_u32 v74, v23, v74, s26
	global_store_short_d16_hi v71, v74, s[38:39] offset:2048
	v_bfe_u32 v75, v6, 16, 1
	v_add3_u32 v75, v6, v75, s26
	global_store_short_d16_hi v71, v75, s[38:39] offset:128
	v_bfe_u32 v76, v7, 16, 1
	v_add3_u32 v76, v7, v76, s26
	global_store_short_d16_hi v71, v76, s[38:39] offset:2176
	v_add_u32_e32 v72, 0x15000, v70
	v_bfe_u32 v77, v24, 16, 1
	v_add3_u32 v77, v24, v77, s26
	global_store_short_d16_hi v72, v77, s[38:39]
	v_bfe_u32 v78, v25, 16, 1
	v_add3_u32 v78, v25, v78, s26
	global_store_short_d16_hi v72, v78, s[38:39] offset:2048
	v_bfe_u32 v79, v8, 16, 1
	v_add3_u32 v79, v8, v79, s26
	global_store_short_d16_hi v72, v79, s[38:39] offset:128
	v_bfe_u32 v80, v9, 16, 1
	v_add3_u32 v80, v9, v80, s26
	global_store_short_d16_hi v72, v80, s[38:39] offset:2176
	v_add_u32_e32 v71, 0x18000, v70
	v_bfe_u32 v73, v26, 16, 1
	v_add3_u32 v73, v26, v73, s26
	global_store_short_d16_hi v71, v73, s[38:39]
	v_bfe_u32 v74, v27, 16, 1
	v_add3_u32 v74, v27, v74, s26
	global_store_short_d16_hi v71, v74, s[38:39] offset:2048
	v_bfe_u32 v75, v10, 16, 1
	v_add3_u32 v75, v10, v75, s26
	global_store_short_d16_hi v71, v75, s[38:39] offset:128
	v_bfe_u32 v76, v11, 16, 1
	v_add3_u32 v76, v11, v76, s26
	global_store_short_d16_hi v71, v76, s[38:39] offset:2176
	v_add_u32_e32 v72, 0x19000, v70
	v_bfe_u32 v77, v28, 16, 1
	v_add3_u32 v77, v28, v77, s26
	global_store_short_d16_hi v72, v77, s[38:39]
	v_bfe_u32 v78, v29, 16, 1
	v_add3_u32 v78, v29, v78, s26
	global_store_short_d16_hi v72, v78, s[38:39] offset:2048
	v_bfe_u32 v79, v12, 16, 1
	v_add3_u32 v79, v12, v79, s26
	global_store_short_d16_hi v72, v79, s[38:39] offset:128
	v_bfe_u32 v80, v13, 16, 1
	v_add3_u32 v80, v13, v80, s26
	global_store_short_d16_hi v72, v80, s[38:39] offset:2176
	v_add_u32_e32 v71, 0x1c000, v70
	v_bfe_u32 v73, v30, 16, 1
	v_add3_u32 v73, v30, v73, s26
	global_store_short_d16_hi v71, v73, s[38:39]
	v_bfe_u32 v74, v31, 16, 1
	v_add3_u32 v74, v31, v74, s26
	global_store_short_d16_hi v71, v74, s[38:39] offset:2048
	v_bfe_u32 v75, v14, 16, 1
	v_add3_u32 v75, v14, v75, s26
	global_store_short_d16_hi v71, v75, s[38:39] offset:128
	v_bfe_u32 v76, v15, 16, 1
	v_add3_u32 v76, v15, v76, s26
	global_store_short_d16_hi v71, v76, s[38:39] offset:2176
	v_add_u32_e32 v72, 0x1d000, v70
	v_bfe_u32 v77, v32, 16, 1
	v_add3_u32 v77, v32, v77, s26
	global_store_short_d16_hi v72, v77, s[38:39]
	v_bfe_u32 v78, v33, 16, 1
	v_add3_u32 v78, v33, v78, s26
	global_store_short_d16_hi v72, v78, s[38:39] offset:2048
	v_bfe_u32 v79, v16, 16, 1
	v_add3_u32 v79, v16, v79, s26
	global_store_short_d16_hi v72, v79, s[38:39] offset:128
	v_bfe_u32 v80, v17, 16, 1
	v_add3_u32 v80, v17, v80, s26
	global_store_short_d16_hi v72, v80, s[38:39] offset:2176
	s_nop 0
	v_readlane_b32 s38, v252, 2
	v_readlane_b32 s39, v252, 3
	s_load_dword s11, s[38:39], 0x0
	s_waitcnt lgkmcnt(0)
	s_add_i32 s16, s11, s16
	s_cmpk_gt_i32 s16, 0x1ff
	s_cbranch_scc0 .LBB0_88

.LBB0_491:
	s_lshl_b32 s1, s6, 1
	s_and_b32 s1, s1, 0xffffff80
	v_add_u32_e32 v6, s1, v80
	v_min_i32_e32 v4, 0xa2f, v6
	v_ashrrev_i32_e32 v5, 31, v4
	v_lshlrev_b64 v[4:5], 11, v[4:5]
	v_lshl_add_u64 v[70:71], v[68:69], 0, v[4:5]
	v_add_u32_e32 v4, 32, v6
	s_lshl_b32 s0, s6, 7
	v_min_i32_e32 v4, 0xa2f, v4
	s_and_b32 s0, s0, 0x1f80
	v_ashrrev_i32_e32 v5, 31, v4
	v_add_u32_e32 v2, s0, v80
	v_lshlrev_b64 v[4:5], 11, v[4:5]
	v_ashrrev_i32_e32 v3, 31, v2
	v_lshl_add_u64 v[72:73], v[68:69], 0, v[4:5]
	v_add_u32_e32 v4, 64, v6
	v_lshlrev_b64 v[2:3], 11, v[2:3]
	v_min_i32_e32 v4, 0xa2f, v4
	v_readfirstlane_b32 s22, v83
	v_add_u32_e32 v137, 0x8000, v83
	v_ashrrev_i32_e32 v5, 31, v4
	v_lshl_add_u64 v[78:79], v[66:67], 0, v[2:3]
	s_mov_b32 m0, s22
	v_readfirstlane_b32 s24, v137
	v_add_u32_e32 v138, 0x1000, v83
	v_lshlrev_b64 v[4:5], 11, v[4:5]
	global_load_lds_dwordx4 v[78:79], off
	s_mov_b32 m0, s24
	s_mov_b64 s[4:5], 0x10000
	v_readfirstlane_b32 s25, v138
	v_add_u32_e32 v139, 0x9000, v83
	v_lshl_add_u64 v[74:75], v[68:69], 0, v[4:5]
	v_add_u32_e32 v4, 0x60, v6
	global_load_lds_dwordx4 v[70:71], off
	v_lshl_add_u64 v[2:3], v[78:79], 0, s[4:5]
	s_mov_b32 m0, s25
	v_readfirstlane_b32 s27, v139
	v_add_u32_e32 v140, 0x2000, v83
	v_min_i32_e32 v4, 0xa2f, v4
	global_load_lds_dwordx4 v[2:3], off
	s_mov_b32 m0, s27
	s_mov_b64 s[4:5], 0x20000
	v_readfirstlane_b32 s36, v140
	v_add_u32_e32 v134, 0xa000, v83
	v_ashrrev_i32_e32 v5, 31, v4
	global_load_lds_dwordx4 v[72:73], off
	v_lshl_add_u64 v[2:3], v[78:79], 0, s[4:5]
	s_mov_b32 m0, s36
	v_readfirstlane_b32 s37, v134
	v_add_u32_e32 v136, 0x3000, v83
	v_lshlrev_b64 v[4:5], 11, v[4:5]
	global_load_lds_dwordx4 v[2:3], off
	s_mov_b32 m0, s37
	s_mov_b64 s[4:5], 0x30000
	v_readfirstlane_b32 s38, v136
	v_add_u32_e32 v135, 0xb000, v83
	v_lshl_add_u64 v[76:77], v[68:69], 0, v[4:5]
	global_load_lds_dwordx4 v[74:75], off
	v_lshl_add_u64 v[2:3], v[78:79], 0, s[4:5]
	s_mov_b32 m0, s38
	v_readfirstlane_b32 s39, v135
	v_add_u32_e32 v4, 0x4000, v83
	global_load_lds_dwordx4 v[2:3], off
	s_mov_b32 m0, s39
	v_readfirstlane_b32 s4, v4
	v_add_u32_e32 v4, 0xc000, v83
	global_load_lds_dwordx4 v[76:77], off
	v_lshl_add_u64 v[2:3], v[78:79], 0, s[98:99]
	s_mov_b32 m0, s4
	v_readfirstlane_b32 s5, v4
	v_add_u32_e32 v4, 0x5000, v83
	s_waitcnt vmcnt(0)
	s_waitcnt vmcnt(0) lgkmcnt(0)
	s_barrier
	v_readlane_b32 s24, v255, 48
	s_cmp_eq_u32 s24, 1
	s_cbranch_scc1 .Lg0_pair
	v_mov_b32_e32 v2, 0
	v_mov_b32_e32 v3, 0
	v_mov_b32_e32 v4, 0
	v_mov_b32_e32 v5, 0
	v_mov_b32_e32 v6, 0
	v_mov_b32_e32 v7, 0
	v_mov_b32_e32 v8, 0
	v_mov_b32_e32 v9, 0
	v_mov_b32_e32 v10, 0
	v_mov_b32_e32 v11, 0
	v_mov_b32_e32 v12, 0
	v_mov_b32_e32 v13, 0
	v_mov_b32_e32 v14, 0
	v_mov_b32_e32 v15, 0
	v_mov_b32_e32 v16, 0
	v_mov_b32_e32 v17, 0
	v_mov_b32_e32 v18, 0
	v_mov_b32_e32 v19, 0
	v_mov_b32_e32 v20, 0
	v_mov_b32_e32 v21, 0
	v_mov_b32_e32 v22, 0
	v_mov_b32_e32 v23, 0
	v_mov_b32_e32 v24, 0
	v_mov_b32_e32 v25, 0
	v_mov_b32_e32 v26, 0
	v_mov_b32_e32 v27, 0
	v_mov_b32_e32 v28, 0
	v_mov_b32_e32 v29, 0
	v_mov_b32_e32 v30, 0
	v_mov_b32_e32 v31, 0
	v_mov_b32_e32 v32, 0
	v_mov_b32_e32 v33, 0
	v_mov_b32_e32 v34, 0
	v_mov_b32_e32 v35, 0
	v_mov_b32_e32 v36, 0
	v_mov_b32_e32 v37, 0
	v_mov_b32_e32 v38, 0
	v_mov_b32_e32 v39, 0
	v_mov_b32_e32 v40, 0
	v_mov_b32_e32 v41, 0
	v_mov_b32_e32 v42, 0
	v_mov_b32_e32 v43, 0
	v_mov_b32_e32 v44, 0
	v_mov_b32_e32 v45, 0
	v_mov_b32_e32 v46, 0
	v_mov_b32_e32 v47, 0
	v_mov_b32_e32 v48, 0
	v_mov_b32_e32 v49, 0
	v_mov_b32_e32 v50, 0
	v_mov_b32_e32 v51, 0
	v_mov_b32_e32 v52, 0
	v_mov_b32_e32 v53, 0
	v_mov_b32_e32 v54, 0
	v_mov_b32_e32 v55, 0
	v_mov_b32_e32 v56, 0
	v_mov_b32_e32 v57, 0
	v_mov_b32_e32 v58, 0
	v_mov_b32_e32 v59, 0
	v_mov_b32_e32 v60, 0
	v_mov_b32_e32 v61, 0
	v_mov_b32_e32 v62, 0
	v_mov_b32_e32 v63, 0
	v_mov_b32_e32 v64, 0
	v_mov_b32_e32 v65, 0
	v_lshl_add_u64 v[164:165], v[78:79], 0, s[98:99]
	s_mov_b64 s[10:11], 0x10080
	v_lshl_add_u64 v[166:167], v[78:79], 0, s[10:11]
	s_mov_b64 s[10:11], 0x20080
	v_lshl_add_u64 v[168:169], v[78:79], 0, s[10:11]
	s_mov_b64 s[10:11], 0x30080
	v_lshl_add_u64 v[170:171], v[78:79], 0, s[10:11]
	v_lshl_add_u64 v[172:173], v[70:71], 0, s[98:99]
	v_lshl_add_u64 v[174:175], v[72:73], 0, s[98:99]
	v_lshl_add_u64 v[176:177], v[74:75], 0, s[98:99]
	v_lshl_add_u64 v[178:179], v[76:77], 0, s[98:99]
	v_add_u32_e32 v222, v119, v85
	v_add_u32_e32 v223, v118, v85
	v_add_u32_e32 v224, v117, v85
	v_add_u32_e32 v225, v116, v85
	s_mov_b32 s24, 7
	ds_read_b128 v[180:183], v120
	ds_read_b128 v[184:187], v120 offset:4096
	ds_read_b128 v[188:191], v222 offset:32768
	ds_read_b128 v[192:195], v222 offset:40960
	v_readlane_b32 s100, v255, 49
	s_cmp_eq_u32 s100, -1
	s_cbranch_scc1 .Lstag_g0
	s_bitcmp1_b32 s100, 8
	s_cbranch_scc0 .Lstag_g0
	s_sleep 8
.Lstag_g0:
.Lg0_loop:
	ds_read_b128 v[206:209], v121
	ds_read_b128 v[210:213], v121 offset:4096
	ds_read_b128 v[214:217], v223 offset:32768
	ds_read_b128 v[218:221], v223 offset:40960
	s_waitcnt lgkmcnt(4)
	v_mfma_f32_32x32x16_bf16 v[50:65], v[180:183], v[188:191], v[50:65]
	s_add_u32 m0, s22, 0x4000
	s_nop 0
	global_load_lds_dwordx4 v[164:165], off
	v_lshl_add_u64 v[164:165], v[164:165], 0, s[98:99]
	v_mfma_f32_32x32x16_bf16 v[34:49], v[180:183], v[192:195], v[34:49]
	s_add_u32 m0, s22, 0xc000
	s_nop 0
	global_load_lds_dwordx4 v[172:173], off
	v_lshl_add_u64 v[172:173], v[172:173], 0, s[98:99]
	v_mfma_f32_32x32x16_bf16 v[18:33], v[184:187], v[188:191], v[18:33]
	s_add_u32 m0, s22, 0x5000
	s_nop 0
	global_load_lds_dwordx4 v[166:167], off
	v_lshl_add_u64 v[166:167], v[166:167], 0, s[98:99]
	v_mfma_f32_32x32x16_bf16 v[2:17], v[184:187], v[192:195], v[2:17]
	ds_read_b128 v[180:183], v122
	ds_read_b128 v[184:187], v122 offset:4096
	ds_read_b128 v[188:191], v224 offset:32768
	ds_read_b128 v[192:195], v224 offset:40960
	s_waitcnt lgkmcnt(4)
	v_mfma_f32_32x32x16_bf16 v[50:65], v[206:209], v[214:217], v[50:65]
	s_add_u32 m0, s22, 0xd000
	s_nop 0
	global_load_lds_dwordx4 v[174:175], off
	v_lshl_add_u64 v[174:175], v[174:175], 0, s[98:99]
	v_mfma_f32_32x32x16_bf16 v[34:49], v[206:209], v[218:221], v[34:49]
	s_add_u32 m0, s22, 0x6000
	s_nop 0
	global_load_lds_dwordx4 v[168:169], off
	v_lshl_add_u64 v[168:169], v[168:169], 0, s[98:99]
	v_mfma_f32_32x32x16_bf16 v[18:33], v[210:213], v[214:217], v[18:33]
	s_add_u32 m0, s22, 0xe000
	s_nop 0
	global_load_lds_dwordx4 v[176:177], off
	v_lshl_add_u64 v[176:177], v[176:177], 0, s[98:99]
	v_mfma_f32_32x32x16_bf16 v[2:17], v[210:213], v[218:221], v[2:17]
	ds_read_b128 v[206:209], v123
	ds_read_b128 v[210:213], v123 offset:4096
	ds_read_b128 v[214:217], v225 offset:32768
	ds_read_b128 v[218:221], v225 offset:40960
	s_waitcnt lgkmcnt(4)
	v_mfma_f32_32x32x16_bf16 v[50:65], v[180:183], v[188:191], v[50:65]
	s_add_u32 m0, s22, 0x7000
	s_nop 0
	global_load_lds_dwordx4 v[170:171], off
	v_lshl_add_u64 v[170:171], v[170:171], 0, s[98:99]
	v_mfma_f32_32x32x16_bf16 v[34:49], v[180:183], v[192:195], v[34:49]
	s_add_u32 m0, s22, 0xf000
	s_nop 0
	global_load_lds_dwordx4 v[178:179], off
	v_lshl_add_u64 v[178:179], v[178:179], 0, s[98:99]
	v_mfma_f32_32x32x16_bf16 v[18:33], v[184:187], v[188:191], v[18:33]
	v_mfma_f32_32x32x16_bf16 v[2:17], v[184:187], v[192:195], v[2:17]
	s_waitcnt vmcnt(0) lgkmcnt(0)
	s_barrier
	ds_read_b128 v[180:183], v120 offset:16384
	ds_read_b128 v[184:187], v120 offset:20480
	ds_read_b128 v[188:191], v222 offset:49152
	ds_read_b128 v[192:195], v222 offset:57344
	v_mfma_f32_32x32x16_bf16 v[50:65], v[206:209], v[214:217], v[50:65]
	v_mfma_f32_32x32x16_bf16 v[34:49], v[206:209], v[218:221], v[34:49]
	v_mfma_f32_32x32x16_bf16 v[18:33], v[210:213], v[214:217], v[18:33]
	v_mfma_f32_32x32x16_bf16 v[2:17], v[210:213], v[218:221], v[2:17]
	ds_read_b128 v[206:209], v121 offset:16384
	ds_read_b128 v[210:213], v121 offset:20480
	ds_read_b128 v[214:217], v223 offset:49152
	ds_read_b128 v[218:221], v223 offset:57344
	s_waitcnt lgkmcnt(4)
	v_mfma_f32_32x32x16_bf16 v[50:65], v[180:183], v[188:191], v[50:65]
	s_mov_b32 m0, s22
	s_nop 0
	global_load_lds_dwordx4 v[164:165], off
	v_lshl_add_u64 v[164:165], v[164:165], 0, s[98:99]
	v_mfma_f32_32x32x16_bf16 v[34:49], v[180:183], v[192:195], v[34:49]
	s_add_u32 m0, s22, 0x8000
	s_nop 0
	global_load_lds_dwordx4 v[172:173], off
	v_lshl_add_u64 v[172:173], v[172:173], 0, s[98:99]
	v_mfma_f32_32x32x16_bf16 v[18:33], v[184:187], v[188:191], v[18:33]
	s_add_u32 m0, s22, 0x1000
	s_nop 0
	global_load_lds_dwordx4 v[166:167], off
	v_lshl_add_u64 v[166:167], v[166:167], 0, s[98:99]
	v_mfma_f32_32x32x16_bf16 v[2:17], v[184:187], v[192:195], v[2:17]
	ds_read_b128 v[180:183], v122 offset:16384
	ds_read_b128 v[184:187], v122 offset:20480
	ds_read_b128 v[188:191], v224 offset:49152
	ds_read_b128 v[192:195], v224 offset:57344
	s_waitcnt lgkmcnt(4)
	v_mfma_f32_32x32x16_bf16 v[50:65], v[206:209], v[214:217], v[50:65]
	s_add_u32 m0, s22, 0x9000
	s_nop 0
	global_load_lds_dwordx4 v[174:175], off
	v_lshl_add_u64 v[174:175], v[174:175], 0, s[98:99]
	v_mfma_f32_32x32x16_bf16 v[34:49], v[206:209], v[218:221], v[34:49]
	s_add_u32 m0, s22, 0x2000
	s_nop 0
	global_load_lds_dwordx4 v[168:169], off
	v_lshl_add_u64 v[168:169], v[168:169], 0, s[98:99]
	v_mfma_f32_32x32x16_bf16 v[18:33], v[210:213], v[214:217], v[18:33]
	s_add_u32 m0, s22, 0xa000
	s_nop 0
	global_load_lds_dwordx4 v[176:177], off
	v_lshl_add_u64 v[176:177], v[176:177], 0, s[98:99]
	v_mfma_f32_32x32x16_bf16 v[2:17], v[210:213], v[218:221], v[2:17]
	ds_read_b128 v[206:209], v123 offset:16384
	ds_read_b128 v[210:213], v123 offset:20480
	ds_read_b128 v[214:217], v225 offset:49152
	ds_read_b128 v[218:221], v225 offset:57344
	s_waitcnt lgkmcnt(4)
	v_mfma_f32_32x32x16_bf16 v[50:65], v[180:183], v[188:191], v[50:65]
	s_add_u32 m0, s22, 0x3000
	s_nop 0
	global_load_lds_dwordx4 v[170:171], off
	v_lshl_add_u64 v[170:171], v[170:171], 0, s[98:99]
	v_mfma_f32_32x32x16_bf16 v[34:49], v[180:183], v[192:195], v[34:49]
	s_add_u32 m0, s22, 0xb000
	s_nop 0
	global_load_lds_dwordx4 v[178:179], off
	v_lshl_add_u64 v[178:179], v[178:179], 0, s[98:99]
	v_mfma_f32_32x32x16_bf16 v[18:33], v[184:187], v[188:191], v[18:33]
	v_mfma_f32_32x32x16_bf16 v[2:17], v[184:187], v[192:195], v[2:17]
	s_waitcnt vmcnt(0) lgkmcnt(0)
	s_barrier
	ds_read_b128 v[180:183], v120
	ds_read_b128 v[184:187], v120 offset:4096
	ds_read_b128 v[188:191], v222 offset:32768
	ds_read_b128 v[192:195], v222 offset:40960
	v_mfma_f32_32x32x16_bf16 v[50:65], v[206:209], v[214:217], v[50:65]
	v_mfma_f32_32x32x16_bf16 v[34:49], v[206:209], v[218:221], v[34:49]
	v_mfma_f32_32x32x16_bf16 v[18:33], v[210:213], v[214:217], v[18:33]
	v_mfma_f32_32x32x16_bf16 v[2:17], v[210:213], v[218:221], v[2:17]
	s_sub_u32 s24, s24, 1
	s_cmp_lg_u32 s24, 0
	s_cbranch_scc1 .Lg0_loop
	ds_read_b128 v[206:209], v121
	ds_read_b128 v[210:213], v121 offset:4096
	ds_read_b128 v[214:217], v223 offset:32768
	ds_read_b128 v[218:221], v223 offset:40960
	s_waitcnt lgkmcnt(4)
	v_mfma_f32_32x32x16_bf16 v[50:65], v[180:183], v[188:191], v[50:65]
	s_add_u32 m0, s22, 0x4000
	s_nop 0
	global_load_lds_dwordx4 v[164:165], off
	v_lshl_add_u64 v[164:165], v[164:165], 0, s[98:99]
	v_mfma_f32_32x32x16_bf16 v[34:49], v[180:183], v[192:195], v[34:49]
	s_add_u32 m0, s22, 0xc000
	s_nop 0
	global_load_lds_dwordx4 v[172:173], off
	v_lshl_add_u64 v[172:173], v[172:173], 0, s[98:99]
	v_mfma_f32_32x32x16_bf16 v[18:33], v[184:187], v[188:191], v[18:33]
	s_add_u32 m0, s22, 0x5000
	s_nop 0
	global_load_lds_dwordx4 v[166:167], off
	v_lshl_add_u64 v[166:167], v[166:167], 0, s[98:99]
	v_mfma_f32_32x32x16_bf16 v[2:17], v[184:187], v[192:195], v[2:17]
	ds_read_b128 v[180:183], v122
	ds_read_b128 v[184:187], v122 offset:4096
	ds_read_b128 v[188:191], v224 offset:32768
	ds_read_b128 v[192:195], v224 offset:40960
	s_waitcnt lgkmcnt(4)
	v_mfma_f32_32x32x16_bf16 v[50:65], v[206:209], v[214:217], v[50:65]
	s_add_u32 m0, s22, 0xd000
	s_nop 0
	global_load_lds_dwordx4 v[174:175], off
	v_lshl_add_u64 v[174:175], v[174:175], 0, s[98:99]
	v_mfma_f32_32x32x16_bf16 v[34:49], v[206:209], v[218:221], v[34:49]
	s_add_u32 m0, s22, 0x6000
	s_nop 0
	global_load_lds_dwordx4 v[168:169], off
	v_lshl_add_u64 v[168:169], v[168:169], 0, s[98:99]
	v_mfma_f32_32x32x16_bf16 v[18:33], v[210:213], v[214:217], v[18:33]
	s_add_u32 m0, s22, 0xe000
	s_nop 0
	global_load_lds_dwordx4 v[176:177], off
	v_lshl_add_u64 v[176:177], v[176:177], 0, s[98:99]
	v_mfma_f32_32x32x16_bf16 v[2:17], v[210:213], v[218:221], v[2:17]
	ds_read_b128 v[206:209], v123
	ds_read_b128 v[210:213], v123 offset:4096
	ds_read_b128 v[214:217], v225 offset:32768
	ds_read_b128 v[218:221], v225 offset:40960
	s_waitcnt lgkmcnt(4)
	v_mfma_f32_32x32x16_bf16 v[50:65], v[180:183], v[188:191], v[50:65]
	s_add_u32 m0, s22, 0x7000
	s_nop 0
	global_load_lds_dwordx4 v[170:171], off
	v_lshl_add_u64 v[170:171], v[170:171], 0, s[98:99]
	v_mfma_f32_32x32x16_bf16 v[34:49], v[180:183], v[192:195], v[34:49]
	s_add_u32 m0, s22, 0xf000
	s_nop 0
	global_load_lds_dwordx4 v[178:179], off
	v_lshl_add_u64 v[178:179], v[178:179], 0, s[98:99]
	v_mfma_f32_32x32x16_bf16 v[18:33], v[184:187], v[188:191], v[18:33]
	v_mfma_f32_32x32x16_bf16 v[2:17], v[184:187], v[192:195], v[2:17]
	s_waitcnt vmcnt(0) lgkmcnt(0)
	s_barrier
	ds_read_b128 v[180:183], v120 offset:16384
	ds_read_b128 v[184:187], v120 offset:20480
	ds_read_b128 v[188:191], v222 offset:49152
	ds_read_b128 v[192:195], v222 offset:57344
	v_mfma_f32_32x32x16_bf16 v[50:65], v[206:209], v[214:217], v[50:65]
	v_mfma_f32_32x32x16_bf16 v[34:49], v[206:209], v[218:221], v[34:49]
	v_mfma_f32_32x32x16_bf16 v[18:33], v[210:213], v[214:217], v[18:33]
	v_mfma_f32_32x32x16_bf16 v[2:17], v[210:213], v[218:221], v[2:17]
	ds_read_b128 v[206:209], v121 offset:16384
	ds_read_b128 v[210:213], v121 offset:20480
	ds_read_b128 v[214:217], v223 offset:49152
	ds_read_b128 v[218:221], v223 offset:57344
	s_waitcnt lgkmcnt(4)
	v_mfma_f32_32x32x16_bf16 v[50:65], v[180:183], v[188:191], v[50:65]
	v_mfma_f32_32x32x16_bf16 v[34:49], v[180:183], v[192:195], v[34:49]
	v_mfma_f32_32x32x16_bf16 v[18:33], v[184:187], v[188:191], v[18:33]
	v_mfma_f32_32x32x16_bf16 v[2:17], v[184:187], v[192:195], v[2:17]
	ds_read_b128 v[180:183], v122 offset:16384
	ds_read_b128 v[184:187], v122 offset:20480
	ds_read_b128 v[188:191], v224 offset:49152
	ds_read_b128 v[192:195], v224 offset:57344
	s_waitcnt lgkmcnt(4)
	v_mfma_f32_32x32x16_bf16 v[50:65], v[206:209], v[214:217], v[50:65]
	v_mfma_f32_32x32x16_bf16 v[34:49], v[206:209], v[218:221], v[34:49]
	v_mfma_f32_32x32x16_bf16 v[18:33], v[210:213], v[214:217], v[18:33]
	v_mfma_f32_32x32x16_bf16 v[2:17], v[210:213], v[218:221], v[2:17]
	ds_read_b128 v[206:209], v123 offset:16384
	ds_read_b128 v[210:213], v123 offset:20480
	ds_read_b128 v[214:217], v225 offset:49152
	ds_read_b128 v[218:221], v225 offset:57344
	s_waitcnt lgkmcnt(4)
	v_mfma_f32_32x32x16_bf16 v[50:65], v[180:183], v[188:191], v[50:65]
	v_mfma_f32_32x32x16_bf16 v[34:49], v[180:183], v[192:195], v[34:49]
	v_mfma_f32_32x32x16_bf16 v[18:33], v[184:187], v[188:191], v[18:33]
	v_mfma_f32_32x32x16_bf16 v[2:17], v[184:187], v[192:195], v[2:17]
	s_waitcnt vmcnt(0) lgkmcnt(0)
	s_barrier
	v_mfma_f32_32x32x16_bf16 v[50:65], v[206:209], v[214:217], v[50:65]
	v_mfma_f32_32x32x16_bf16 v[34:49], v[206:209], v[218:221], v[34:49]
	v_mfma_f32_32x32x16_bf16 v[18:33], v[210:213], v[214:217], v[18:33]
	v_mfma_f32_32x32x16_bf16 v[2:17], v[210:213], v[218:221], v[2:17]
	s_branch .Lg0_join
